# rwkv scan: converter waves run two chunks ahead; compute waves prefetch next chunk's first two steps' operands before the chunk barrier and carry the partial sa across chunks (4 rotating operand sets)
# baseline (speedup 1.0000x reference)
; #define GAS __attribute__((address_space(1)))
; template <int MODE>
; __device__ __forceinline__ void rwkv_scan_unit(int wid_s, const bf16* SIbh_, bf16* Yb_, int ystride, int quarter, float* ldsf) {
;     ...
;     if (wv >= 4 && wv < 7) {
; #pragma unroll
;         for (int i = 0; i < 12; ++i) hreg[i] = *(const GAS u32x4*)(SIbh + (size_t)hw * (16 * 384) + (size_t)(lane + 64 * i) * 8);
;     }
;     f32x2 Sa = {0.f, 0.f}, Sb = {0.f, 0.f};
;     const int rowl = quarter * 16 + (wv & 3) * 4 + (lane >> 4), c4 = (lane & 15) * 4;
;     __syncthreads();
;     ...
;     if (wv == 4) SCAN_CONVERT(0);
.LBB0_1396:
	s_or_b64 exec, exec, s[2:3]
	v_subrev_u32_e32 v49, 4, v54
	v_cmp_lt_u32_e32 vcc, 1, v49
	v_lshrrev_b32_e32 v144, 5, v52
	v_mul_u32_u24_e32 v144, 0xc00, v144
	v_and_b32_e32 v49, 31, v52
	v_lshl_add_u32 v144, v49, 1, v144
	s_waitcnt vmcnt(0) lgkmcnt(0)
	s_barrier
	s_and_saveexec_b64 s[2:3], vcc
	s_xor_b64 s[2:3], exec, s[2:3]
	v_mov_b64_e32 v[50:51], v[144:145]
	s_or_saveexec_b64 s[2:3], s[2:3]
	v_lshlrev_b32_e32 v49, 5, v52
	v_add_u32_e32 v57, 0, v49
	s_xor_b64 exec, exec, s[2:3]
	s_cbranch_execz .LBB0_1400
	v_readfirstlane_b32 s16, v56
	s_mul_i32 s14, s16, 0x3000
	s_mulk_i32 s16, 0x6000
	v_mov_b32_e32 v98, 1.0
	v_lshrrev_b32_e32 v63, 10, v57
	v_mul_u32_u24_e32 v63, 0x3000, v63
	v_bfe_u32 v99, v57, 5, 5
	v_lshl_add_u32 v63, v99, 3, v63
	v_add_u32_e32 v63, s16, v63
	v_mov_b32_e32 v72, 1.0
	v_mov_b32_e32 v73, 1.0
	v_lshlrev_b32_e32 v78, 16, v80
	v_and_b32_e32 v79, 0xffff0000, v80
	v_sub_f32_e32 v78, 1.0, v78
	v_sub_f32_e32 v79, 1.0, v79
	v_mul_f32_e32 v72, v72, v78
	v_mul_f32_e32 v73, v73, v79
	v_lshlrev_b32_e32 v78, 16, v81
	v_and_b32_e32 v79, 0xffff0000, v81
	v_sub_f32_e32 v78, 1.0, v78
	v_sub_f32_e32 v79, 1.0, v79
	v_mul_f32_e32 v72, v72, v78
	v_mul_f32_e32 v73, v73, v79
	v_lshlrev_b32_e32 v78, 16, v82
	v_and_b32_e32 v79, 0xffff0000, v82
	v_sub_f32_e32 v78, 1.0, v78
	v_sub_f32_e32 v79, 1.0, v79
	v_mul_f32_e32 v72, v72, v78
	v_mul_f32_e32 v73, v73, v79
	v_lshlrev_b32_e32 v78, 16, v83
	v_and_b32_e32 v79, 0xffff0000, v83
	v_sub_f32_e32 v78, 1.0, v78
	v_sub_f32_e32 v79, 1.0, v79
	v_mul_f32_e32 v72, v72, v78
	v_mul_f32_e32 v73, v73, v79
	v_lshlrev_b32_e32 v78, 16, v84
	v_and_b32_e32 v79, 0xffff0000, v84
	v_sub_f32_e32 v78, 1.0, v78
	v_sub_f32_e32 v79, 1.0, v79
	v_mul_f32_e32 v72, v72, v78
	v_mul_f32_e32 v73, v73, v79
	v_lshlrev_b32_e32 v78, 16, v85
	v_and_b32_e32 v79, 0xffff0000, v85
	v_sub_f32_e32 v78, 1.0, v78
	v_sub_f32_e32 v79, 1.0, v79
	v_mul_f32_e32 v72, v72, v78
	v_mul_f32_e32 v73, v73, v79
	v_lshlrev_b32_e32 v78, 16, v86
	v_and_b32_e32 v79, 0xffff0000, v86
	v_sub_f32_e32 v78, 1.0, v78
	v_sub_f32_e32 v79, 1.0, v79
	v_mul_f32_e32 v72, v72, v78
	v_mul_f32_e32 v73, v73, v79
	v_lshlrev_b32_e32 v78, 16, v87
	v_and_b32_e32 v79, 0xffff0000, v87
	v_sub_f32_e32 v78, 1.0, v78
	v_sub_f32_e32 v79, 1.0, v79
	v_mul_f32_e32 v72, v72, v78
	v_mul_f32_e32 v73, v73, v79
	v_cmp_gt_u32_e32 vcc, 0x400, v57
	s_nop 1
	v_cndmask_b32_e32 v72, v72, v98, vcc
	v_cndmask_b32_e32 v73, v73, v98, vcc
	v_lshlrev_b32_e32 v78, 16, v1
	v_and_b32_e32 v79, 0xffff0000, v1
	v_sub_f32_e32 v78, 1.0, v78
	v_sub_f32_e32 v79, 1.0, v79
	v_mul_f32_e32 v74, v72, v78
	v_mul_f32_e32 v75, v73, v79
	v_lshlrev_b32_e32 v88, 16, v3
	v_and_b32_e32 v89, 0xffff0000, v3
	v_rcp_f32_e32 v76, v74
	v_rcp_f32_e32 v77, v75
	v_mul_f32_e32 v88, v88, v72
	v_mul_f32_e32 v89, v89, v73
	v_lshlrev_b32_e32 v90, 16, v0
	v_and_b32_e32 v91, 0xffff0000, v0
	v_mul_f32_e32 v90, v90, v74
	v_mul_f32_e32 v91, v91, v75
	v_lshlrev_b32_e32 v92, 16, v2
	v_and_b32_e32 v93, 0xffff0000, v2
	v_mul_f32_e32 v92, v92, v76
	v_mul_f32_e32 v93, v93, v77
	v_lshlrev_b32_e32 v94, 16, v4
	v_and_b32_e32 v95, 0xffff0000, v4
	v_mul_f32_e32 v94, v94, v76
	v_mul_f32_e32 v95, v95, v77
	v_lshlrev_b32_e32 v96, 16, v5
	v_and_b32_e32 v97, 0xffff0000, v5
	ds_write_b64 v63, v[90:91]
	ds_write_b64 v63, v[74:75] offset:256
	ds_write_b64 v63, v[92:93] offset:512
	ds_write_b64 v63, v[88:89] offset:768
	ds_write_b64 v63, v[94:95] offset:1024
	ds_write_b64 v63, v[96:97] offset:1280
	v_mov_b32_e32 v72, v74
	v_mov_b32_e32 v73, v75
	v_lshlrev_b32_e32 v78, 16, v7
	v_and_b32_e32 v79, 0xffff0000, v7
	v_sub_f32_e32 v78, 1.0, v78
	v_sub_f32_e32 v79, 1.0, v79
	v_mul_f32_e32 v74, v72, v78
	v_mul_f32_e32 v75, v73, v79
	v_lshlrev_b32_e32 v88, 16, v9
	v_and_b32_e32 v89, 0xffff0000, v9
	v_rcp_f32_e32 v76, v74
	v_rcp_f32_e32 v77, v75
	v_mul_f32_e32 v88, v88, v72
	v_mul_f32_e32 v89, v89, v73
	v_lshlrev_b32_e32 v90, 16, v6
	v_and_b32_e32 v91, 0xffff0000, v6
	v_mul_f32_e32 v90, v90, v74
	v_mul_f32_e32 v91, v91, v75
	v_lshlrev_b32_e32 v92, 16, v8
	v_and_b32_e32 v93, 0xffff0000, v8
	v_mul_f32_e32 v92, v92, v76
	v_mul_f32_e32 v93, v93, v77
	v_lshlrev_b32_e32 v94, 16, v10
	v_and_b32_e32 v95, 0xffff0000, v10
	v_mul_f32_e32 v94, v94, v76
	v_mul_f32_e32 v95, v95, v77
	v_lshlrev_b32_e32 v96, 16, v11
	v_and_b32_e32 v97, 0xffff0000, v11
	ds_write_b64 v63, v[90:91] offset:1536
	ds_write_b64 v63, v[74:75] offset:1792
	ds_write_b64 v63, v[92:93] offset:2048
	ds_write_b64 v63, v[88:89] offset:2304
	ds_write_b64 v63, v[94:95] offset:2560
	ds_write_b64 v63, v[96:97] offset:2816
	v_mov_b32_e32 v72, v74
	v_mov_b32_e32 v73, v75
	v_lshlrev_b32_e32 v78, 16, v13
	v_and_b32_e32 v79, 0xffff0000, v13
	v_sub_f32_e32 v78, 1.0, v78
	v_sub_f32_e32 v79, 1.0, v79
	v_mul_f32_e32 v74, v72, v78
	v_mul_f32_e32 v75, v73, v79
	v_lshlrev_b32_e32 v88, 16, v15
	v_and_b32_e32 v89, 0xffff0000, v15
	v_rcp_f32_e32 v76, v74
	v_rcp_f32_e32 v77, v75
	v_mul_f32_e32 v88, v88, v72
	v_mul_f32_e32 v89, v89, v73
	v_lshlrev_b32_e32 v90, 16, v12
	v_and_b32_e32 v91, 0xffff0000, v12
	v_mul_f32_e32 v90, v90, v74
	v_mul_f32_e32 v91, v91, v75
	v_lshlrev_b32_e32 v92, 16, v14
	v_and_b32_e32 v93, 0xffff0000, v14
	v_mul_f32_e32 v92, v92, v76
	v_mul_f32_e32 v93, v93, v77
	v_lshlrev_b32_e32 v94, 16, v16
	v_and_b32_e32 v95, 0xffff0000, v16
	v_mul_f32_e32 v94, v94, v76
	v_mul_f32_e32 v95, v95, v77
	v_lshlrev_b32_e32 v96, 16, v17
	v_and_b32_e32 v97, 0xffff0000, v17
	ds_write_b64 v63, v[90:91] offset:3072
	ds_write_b64 v63, v[74:75] offset:3328
	ds_write_b64 v63, v[92:93] offset:3584
	ds_write_b64 v63, v[88:89] offset:3840
	ds_write_b64 v63, v[94:95] offset:4096
	ds_write_b64 v63, v[96:97] offset:4352
	v_mov_b32_e32 v72, v74
	v_mov_b32_e32 v73, v75
	v_lshlrev_b32_e32 v78, 16, v19
	v_and_b32_e32 v79, 0xffff0000, v19
	v_sub_f32_e32 v78, 1.0, v78
	v_sub_f32_e32 v79, 1.0, v79
	v_mul_f32_e32 v74, v72, v78
	v_mul_f32_e32 v75, v73, v79
	v_lshlrev_b32_e32 v88, 16, v21
	v_and_b32_e32 v89, 0xffff0000, v21
	v_rcp_f32_e32 v76, v74
	v_rcp_f32_e32 v77, v75
	v_mul_f32_e32 v88, v88, v72
	v_mul_f32_e32 v89, v89, v73
	v_lshlrev_b32_e32 v90, 16, v18
	v_and_b32_e32 v91, 0xffff0000, v18
	v_mul_f32_e32 v90, v90, v74
	v_mul_f32_e32 v91, v91, v75
	v_lshlrev_b32_e32 v92, 16, v20
	v_and_b32_e32 v93, 0xffff0000, v20
	v_mul_f32_e32 v92, v92, v76
	v_mul_f32_e32 v93, v93, v77
	v_lshlrev_b32_e32 v94, 16, v22
	v_and_b32_e32 v95, 0xffff0000, v22
	v_mul_f32_e32 v94, v94, v76
	v_mul_f32_e32 v95, v95, v77
	v_lshlrev_b32_e32 v96, 16, v23
	v_and_b32_e32 v97, 0xffff0000, v23
	ds_write_b64 v63, v[90:91] offset:4608
	ds_write_b64 v63, v[74:75] offset:4864
	ds_write_b64 v63, v[92:93] offset:5120
	ds_write_b64 v63, v[88:89] offset:5376
	ds_write_b64 v63, v[94:95] offset:5632
	ds_write_b64 v63, v[96:97] offset:5888
	v_mov_b32_e32 v72, v74
	v_mov_b32_e32 v73, v75
	v_lshlrev_b32_e32 v78, 16, v25
	v_and_b32_e32 v79, 0xffff0000, v25
	v_sub_f32_e32 v78, 1.0, v78
	v_sub_f32_e32 v79, 1.0, v79
	v_mul_f32_e32 v74, v72, v78
	v_mul_f32_e32 v75, v73, v79
	v_lshlrev_b32_e32 v88, 16, v27
	v_and_b32_e32 v89, 0xffff0000, v27
	v_rcp_f32_e32 v76, v74
	v_rcp_f32_e32 v77, v75
	v_mul_f32_e32 v88, v88, v72
	v_mul_f32_e32 v89, v89, v73
	v_lshlrev_b32_e32 v90, 16, v24
	v_and_b32_e32 v91, 0xffff0000, v24
	v_mul_f32_e32 v90, v90, v74
	v_mul_f32_e32 v91, v91, v75
	v_lshlrev_b32_e32 v92, 16, v26
	v_and_b32_e32 v93, 0xffff0000, v26
	v_mul_f32_e32 v92, v92, v76
	v_mul_f32_e32 v93, v93, v77
	v_lshlrev_b32_e32 v94, 16, v28
	v_and_b32_e32 v95, 0xffff0000, v28
	v_mul_f32_e32 v94, v94, v76
	v_mul_f32_e32 v95, v95, v77
	v_lshlrev_b32_e32 v96, 16, v29
	v_and_b32_e32 v97, 0xffff0000, v29
	ds_write_b64 v63, v[90:91] offset:6144
	ds_write_b64 v63, v[74:75] offset:6400
	ds_write_b64 v63, v[92:93] offset:6656
	ds_write_b64 v63, v[88:89] offset:6912
	ds_write_b64 v63, v[94:95] offset:7168
	ds_write_b64 v63, v[96:97] offset:7424
	v_mov_b32_e32 v72, v74
	v_mov_b32_e32 v73, v75
	v_lshlrev_b32_e32 v78, 16, v31
	v_and_b32_e32 v79, 0xffff0000, v31
	v_sub_f32_e32 v78, 1.0, v78
	v_sub_f32_e32 v79, 1.0, v79
	v_mul_f32_e32 v74, v72, v78
	v_mul_f32_e32 v75, v73, v79
	v_lshlrev_b32_e32 v88, 16, v33
	v_and_b32_e32 v89, 0xffff0000, v33
	v_rcp_f32_e32 v76, v74
	v_rcp_f32_e32 v77, v75
	v_mul_f32_e32 v88, v88, v72
	v_mul_f32_e32 v89, v89, v73
	v_lshlrev_b32_e32 v90, 16, v30
	v_and_b32_e32 v91, 0xffff0000, v30
	v_mul_f32_e32 v90, v90, v74
	v_mul_f32_e32 v91, v91, v75
	v_lshlrev_b32_e32 v92, 16, v32
	v_and_b32_e32 v93, 0xffff0000, v32
	v_mul_f32_e32 v92, v92, v76
	v_mul_f32_e32 v93, v93, v77
	v_lshlrev_b32_e32 v94, 16, v34
	v_and_b32_e32 v95, 0xffff0000, v34
	v_mul_f32_e32 v94, v94, v76
	v_mul_f32_e32 v95, v95, v77
	v_lshlrev_b32_e32 v96, 16, v35
	v_and_b32_e32 v97, 0xffff0000, v35
	ds_write_b64 v63, v[90:91] offset:7680
	ds_write_b64 v63, v[74:75] offset:7936
	ds_write_b64 v63, v[92:93] offset:8192
	ds_write_b64 v63, v[88:89] offset:8448
	ds_write_b64 v63, v[94:95] offset:8704
	ds_write_b64 v63, v[96:97] offset:8960
	v_mov_b32_e32 v72, v74
	v_mov_b32_e32 v73, v75
	v_lshlrev_b32_e32 v78, 16, v37
	v_and_b32_e32 v79, 0xffff0000, v37
	v_sub_f32_e32 v78, 1.0, v78
	v_sub_f32_e32 v79, 1.0, v79
	v_mul_f32_e32 v74, v72, v78
	v_mul_f32_e32 v75, v73, v79
	v_lshlrev_b32_e32 v88, 16, v39
	v_and_b32_e32 v89, 0xffff0000, v39
	v_rcp_f32_e32 v76, v74
	v_rcp_f32_e32 v77, v75
	v_mul_f32_e32 v88, v88, v72
	v_mul_f32_e32 v89, v89, v73
	v_lshlrev_b32_e32 v90, 16, v36
	v_and_b32_e32 v91, 0xffff0000, v36
	v_mul_f32_e32 v90, v90, v74
	v_mul_f32_e32 v91, v91, v75
	v_lshlrev_b32_e32 v92, 16, v38
	v_and_b32_e32 v93, 0xffff0000, v38
	v_mul_f32_e32 v92, v92, v76
	v_mul_f32_e32 v93, v93, v77
	v_lshlrev_b32_e32 v94, 16, v40
	v_and_b32_e32 v95, 0xffff0000, v40
	v_mul_f32_e32 v94, v94, v76
	v_mul_f32_e32 v95, v95, v77
	v_lshlrev_b32_e32 v96, 16, v41
	v_and_b32_e32 v97, 0xffff0000, v41
	ds_write_b64 v63, v[90:91] offset:9216
	ds_write_b64 v63, v[74:75] offset:9472
	ds_write_b64 v63, v[92:93] offset:9728
	ds_write_b64 v63, v[88:89] offset:9984
	ds_write_b64 v63, v[94:95] offset:10240
	ds_write_b64 v63, v[96:97] offset:10496
	v_mov_b32_e32 v72, v74
	v_mov_b32_e32 v73, v75
	v_lshlrev_b32_e32 v78, 16, v43
	v_and_b32_e32 v79, 0xffff0000, v43
	v_sub_f32_e32 v78, 1.0, v78
	v_sub_f32_e32 v79, 1.0, v79
	v_mul_f32_e32 v74, v72, v78
	v_mul_f32_e32 v75, v73, v79
	v_lshlrev_b32_e32 v88, 16, v45
	v_and_b32_e32 v89, 0xffff0000, v45
	v_rcp_f32_e32 v76, v74
	v_rcp_f32_e32 v77, v75
	v_mul_f32_e32 v88, v88, v72
	v_mul_f32_e32 v89, v89, v73
	v_lshlrev_b32_e32 v90, 16, v42
	v_and_b32_e32 v91, 0xffff0000, v42
	v_mul_f32_e32 v90, v90, v74
	v_mul_f32_e32 v91, v91, v75
	v_lshlrev_b32_e32 v92, 16, v44
	v_and_b32_e32 v93, 0xffff0000, v44
	v_mul_f32_e32 v92, v92, v76
	v_mul_f32_e32 v93, v93, v77
	v_lshlrev_b32_e32 v94, 16, v46
	v_and_b32_e32 v95, 0xffff0000, v46
	v_mul_f32_e32 v94, v94, v76
	v_mul_f32_e32 v95, v95, v77
	v_lshlrev_b32_e32 v96, 16, v47
	v_and_b32_e32 v97, 0xffff0000, v47
	ds_write_b64 v63, v[90:91] offset:10752
	ds_write_b64 v63, v[74:75] offset:11008
	ds_write_b64 v63, v[92:93] offset:11264
	ds_write_b64 v63, v[88:89] offset:11520
	ds_write_b64 v63, v[94:95] offset:11776
	ds_write_b64 v63, v[96:97] offset:12032
	v_mov_b32_e32 v72, v74
	v_mov_b32_e32 v73, v75
	v_lshrrev_b32_e32 v66, 5, v52
	v_mul_u32_u24_e32 v66, 0x1800, v66
	v_and_b32_e32 v67, 31, v52
	v_lshlrev_b32_e32 v67, 2, v67
	v_add_u32_e32 v64, v67, v66
	v_mov_b32_e32 v65, 0
	v_mov_b32_e32 v66, v67
	v_mov_b32_e32 v67, 0
	s_add_i32 s12, s14, 0x9000
	s_mov_b32 s13, 0
	v_lshl_add_u64 v[64:65], s[6:7], 0, v[64:65]
	v_lshl_add_u64 v[66:67], s[6:7], 0, v[66:67]
	v_lshl_add_u64 v[64:65], v[64:65], 0, s[12:13]
	v_lshl_add_u64 v[66:67], v[66:67], 0, s[12:13]
	s_movk_i32 s12, 0xf00
	s_mov_b32 s13, 0
	v_lshl_add_u64 v[68:69], v[64:65], 0, s[12:13]
	v_lshl_add_u64 v[70:71], v[66:67], 0, s[12:13]
	global_load_dword v0, v[64:65], off
	global_load_dword v1, v[64:65], off offset:128
	global_load_dword v2, v[64:65], off offset:256
	global_load_dword v3, v[64:65], off offset:384
	global_load_dword v4, v[64:65], off offset:512
	global_load_dword v5, v[64:65], off offset:640
	global_load_dword v6, v[64:65], off offset:768
	global_load_dword v7, v[64:65], off offset:896
	global_load_dword v8, v[64:65], off offset:1024
	global_load_dword v9, v[64:65], off offset:1152
	global_load_dword v10, v[64:65], off offset:1280
	global_load_dword v11, v[64:65], off offset:1408
	global_load_dword v12, v[64:65], off offset:1536
	global_load_dword v13, v[64:65], off offset:1664
	global_load_dword v14, v[64:65], off offset:1792
	global_load_dword v15, v[64:65], off offset:1920
	global_load_dword v16, v[64:65], off offset:2048
	global_load_dword v17, v[64:65], off offset:2176
	global_load_dword v18, v[64:65], off offset:2304
	global_load_dword v19, v[64:65], off offset:2432
	global_load_dword v20, v[64:65], off offset:2560
	global_load_dword v21, v[64:65], off offset:2688
	global_load_dword v22, v[64:65], off offset:2816
	global_load_dword v23, v[64:65], off offset:2944
	global_load_dword v24, v[64:65], off offset:3072
	global_load_dword v25, v[64:65], off offset:3200
	global_load_dword v26, v[64:65], off offset:3328
	global_load_dword v27, v[64:65], off offset:3456
	global_load_dword v28, v[64:65], off offset:3584
	global_load_dword v29, v[64:65], off offset:3712
	global_load_dword v30, v[64:65], off offset:3840
	global_load_dword v31, v[64:65], off offset:3968
	global_load_dword v32, v[68:69], off offset:256
	global_load_dword v33, v[68:69], off offset:384
	global_load_dword v34, v[68:69], off offset:512
	global_load_dword v35, v[68:69], off offset:640
	global_load_dword v36, v[68:69], off offset:768
	global_load_dword v37, v[68:69], off offset:896
	global_load_dword v38, v[68:69], off offset:1024
	global_load_dword v39, v[68:69], off offset:1152
	global_load_dword v40, v[68:69], off offset:1280
	global_load_dword v41, v[68:69], off offset:1408
	global_load_dword v42, v[68:69], off offset:1536
	global_load_dword v43, v[68:69], off offset:1664
	global_load_dword v44, v[68:69], off offset:1792
	global_load_dword v45, v[68:69], off offset:1920
	global_load_dword v46, v[68:69], off offset:2048
	global_load_dword v47, v[68:69], off offset:2176
	global_load_dword v80, v[66:67], off offset:128
	global_load_dword v81, v[66:67], off offset:896
	global_load_dword v82, v[66:67], off offset:1664
	global_load_dword v83, v[66:67], off offset:2432
	global_load_dword v84, v[66:67], off offset:3200
	global_load_dword v85, v[66:67], off offset:3968
	global_load_dword v86, v[70:71], off offset:896
	global_load_dword v87, v[70:71], off offset:1664
	v_mov_b64_e32 v[50:51], v[144:145]

; template <int MODE>
; __device__ __forceinline__ void rwkv_scan_unit(int wid_s, const bf16* SIbh_, bf16* Yb_, int ystride, int quarter, float* ldsf) {
;     ...
;         } else {
;             const int cn = ch + 1;
;             if (cn < 128 && (cn % 3) == hw) SCAN_CONVERT(cn);
;         }
.LBB0_1402:
	s_waitcnt lgkmcnt(0)
	s_barrier
	s_and_saveexec_b64 s[8:9], s[2:3]
	s_xor_b64 s[8:9], exec, s[8:9]
	s_cbranch_execz .LBB0_1412
	s_and_saveexec_b64 s[10:11], s[4:5]
	s_xor_b64 s[10:11], exec, s[10:11]
	s_cbranch_execz .LBB0_1408
	s_add_i32 s14, s0, 2
	v_readfirstlane_b32 s15, v56
	s_mul_i32 s17, s14, 0xab
	s_lshr_b32 s17, s17, 9
	s_mul_i32 s17, s17, 3
	s_sub_i32 s17, s14, s17
	s_cmp_lg_u32 s17, s15
	s_cbranch_scc1 .Lmy_cv_tryA
	s_cmp_gt_u32 s14, 0x7f
	s_cbranch_scc1 .Lmy_cv_done
	s_and_b32 s16, s14, 3
	s_mulk_i32 s16, 0x6000
	v_mov_b32_e32 v98, 1.0
	v_lshrrev_b32_e32 v63, 10, v57
	v_mul_u32_u24_e32 v63, 0x3000, v63
	v_bfe_u32 v99, v57, 5, 5
	v_lshl_add_u32 v63, v99, 3, v63
	v_add_u32_e32 v63, s16, v63
	s_cmp_lg_u32 s14, 2
	s_cbranch_scc1 .Lmy_cv_B
	s_waitcnt vmcnt(0)
	v_mov_b32_e32 v72, 1.0
	v_mov_b32_e32 v73, 1.0
	v_lshlrev_b32_e32 v78, 16, v80
	v_and_b32_e32 v79, 0xffff0000, v80
	v_sub_f32_e32 v78, 1.0, v78
	v_sub_f32_e32 v79, 1.0, v79
	v_mul_f32_e32 v72, v72, v78
	v_mul_f32_e32 v73, v73, v79
	v_lshlrev_b32_e32 v78, 16, v81
	v_and_b32_e32 v79, 0xffff0000, v81
	v_sub_f32_e32 v78, 1.0, v78
	v_sub_f32_e32 v79, 1.0, v79
	v_mul_f32_e32 v72, v72, v78
	v_mul_f32_e32 v73, v73, v79
	v_lshlrev_b32_e32 v78, 16, v82
	v_and_b32_e32 v79, 0xffff0000, v82
	v_sub_f32_e32 v78, 1.0, v78
	v_sub_f32_e32 v79, 1.0, v79
	v_mul_f32_e32 v72, v72, v78
	v_mul_f32_e32 v73, v73, v79
	v_lshlrev_b32_e32 v78, 16, v83
	v_and_b32_e32 v79, 0xffff0000, v83
	v_sub_f32_e32 v78, 1.0, v78
	v_sub_f32_e32 v79, 1.0, v79
	v_mul_f32_e32 v72, v72, v78
	v_mul_f32_e32 v73, v73, v79
	v_lshlrev_b32_e32 v78, 16, v84
	v_and_b32_e32 v79, 0xffff0000, v84
	v_sub_f32_e32 v78, 1.0, v78
	v_sub_f32_e32 v79, 1.0, v79
	v_mul_f32_e32 v72, v72, v78
	v_mul_f32_e32 v73, v73, v79
	v_lshlrev_b32_e32 v78, 16, v85
	v_and_b32_e32 v79, 0xffff0000, v85
	v_sub_f32_e32 v78, 1.0, v78
	v_sub_f32_e32 v79, 1.0, v79
	v_mul_f32_e32 v72, v72, v78
	v_mul_f32_e32 v73, v73, v79
	v_lshlrev_b32_e32 v78, 16, v86
	v_and_b32_e32 v79, 0xffff0000, v86
	v_sub_f32_e32 v78, 1.0, v78
	v_sub_f32_e32 v79, 1.0, v79
	v_mul_f32_e32 v72, v72, v78
	v_mul_f32_e32 v73, v73, v79
	v_lshlrev_b32_e32 v78, 16, v87
	v_and_b32_e32 v79, 0xffff0000, v87
	v_sub_f32_e32 v78, 1.0, v78
	v_sub_f32_e32 v79, 1.0, v79
	v_mul_f32_e32 v72, v72, v78
	v_mul_f32_e32 v73, v73, v79
	v_cmp_gt_u32_e32 vcc, 0x400, v57
	s_nop 1
	v_cndmask_b32_e32 v72, v72, v98, vcc
	v_cndmask_b32_e32 v73, v73, v98, vcc
	v_lshlrev_b32_e32 v78, 16, v1
	v_and_b32_e32 v79, 0xffff0000, v1
	v_sub_f32_e32 v78, 1.0, v78
	v_sub_f32_e32 v79, 1.0, v79
	v_mul_f32_e32 v74, v72, v78
	v_mul_f32_e32 v75, v73, v79
	v_lshlrev_b32_e32 v88, 16, v3
	v_and_b32_e32 v89, 0xffff0000, v3
	v_rcp_f32_e32 v76, v74
	v_rcp_f32_e32 v77, v75
	v_mul_f32_e32 v88, v88, v72
	v_mul_f32_e32 v89, v89, v73
	v_lshlrev_b32_e32 v90, 16, v0
	v_and_b32_e32 v91, 0xffff0000, v0
	v_mul_f32_e32 v90, v90, v74
	v_mul_f32_e32 v91, v91, v75
	v_lshlrev_b32_e32 v92, 16, v2
	v_and_b32_e32 v93, 0xffff0000, v2
	v_mul_f32_e32 v92, v92, v76
	v_mul_f32_e32 v93, v93, v77
	v_lshlrev_b32_e32 v94, 16, v4
	v_and_b32_e32 v95, 0xffff0000, v4
	v_mul_f32_e32 v94, v94, v76
	v_mul_f32_e32 v95, v95, v77
	v_lshlrev_b32_e32 v96, 16, v5
	v_and_b32_e32 v97, 0xffff0000, v5
	ds_write_b64 v63, v[90:91]
	ds_write_b64 v63, v[74:75] offset:256
	ds_write_b64 v63, v[92:93] offset:512
	ds_write_b64 v63, v[88:89] offset:768
	ds_write_b64 v63, v[94:95] offset:1024
	ds_write_b64 v63, v[96:97] offset:1280
	v_mov_b32_e32 v72, v74
	v_mov_b32_e32 v73, v75
	v_lshlrev_b32_e32 v78, 16, v7
	v_and_b32_e32 v79, 0xffff0000, v7
	v_sub_f32_e32 v78, 1.0, v78
	v_sub_f32_e32 v79, 1.0, v79
	v_mul_f32_e32 v74, v72, v78
	v_mul_f32_e32 v75, v73, v79
	v_lshlrev_b32_e32 v88, 16, v9
	v_and_b32_e32 v89, 0xffff0000, v9
	v_rcp_f32_e32 v76, v74
	v_rcp_f32_e32 v77, v75
	v_mul_f32_e32 v88, v88, v72
	v_mul_f32_e32 v89, v89, v73
	v_lshlrev_b32_e32 v90, 16, v6
	v_and_b32_e32 v91, 0xffff0000, v6
	v_mul_f32_e32 v90, v90, v74
	v_mul_f32_e32 v91, v91, v75
	v_lshlrev_b32_e32 v92, 16, v8
	v_and_b32_e32 v93, 0xffff0000, v8
	v_mul_f32_e32 v92, v92, v76
	v_mul_f32_e32 v93, v93, v77
	v_lshlrev_b32_e32 v94, 16, v10
	v_and_b32_e32 v95, 0xffff0000, v10
	v_mul_f32_e32 v94, v94, v76
	v_mul_f32_e32 v95, v95, v77
	v_lshlrev_b32_e32 v96, 16, v11
	v_and_b32_e32 v97, 0xffff0000, v11
	ds_write_b64 v63, v[90:91] offset:1536
	ds_write_b64 v63, v[74:75] offset:1792
	ds_write_b64 v63, v[92:93] offset:2048
	ds_write_b64 v63, v[88:89] offset:2304
	ds_write_b64 v63, v[94:95] offset:2560
	ds_write_b64 v63, v[96:97] offset:2816
	v_mov_b32_e32 v72, v74
	v_mov_b32_e32 v73, v75
	v_lshlrev_b32_e32 v78, 16, v13
	v_and_b32_e32 v79, 0xffff0000, v13
	v_sub_f32_e32 v78, 1.0, v78
	v_sub_f32_e32 v79, 1.0, v79
	v_mul_f32_e32 v74, v72, v78
	v_mul_f32_e32 v75, v73, v79
	v_lshlrev_b32_e32 v88, 16, v15
	v_and_b32_e32 v89, 0xffff0000, v15
	v_rcp_f32_e32 v76, v74
	v_rcp_f32_e32 v77, v75
	v_mul_f32_e32 v88, v88, v72
	v_mul_f32_e32 v89, v89, v73
	v_lshlrev_b32_e32 v90, 16, v12
	v_and_b32_e32 v91, 0xffff0000, v12
	v_mul_f32_e32 v90, v90, v74
	v_mul_f32_e32 v91, v91, v75
	v_lshlrev_b32_e32 v92, 16, v14
	v_and_b32_e32 v93, 0xffff0000, v14
	v_mul_f32_e32 v92, v92, v76
	v_mul_f32_e32 v93, v93, v77
	v_lshlrev_b32_e32 v94, 16, v16
	v_and_b32_e32 v95, 0xffff0000, v16
	v_mul_f32_e32 v94, v94, v76
	v_mul_f32_e32 v95, v95, v77
	v_lshlrev_b32_e32 v96, 16, v17
	v_and_b32_e32 v97, 0xffff0000, v17
	ds_write_b64 v63, v[90:91] offset:3072
	ds_write_b64 v63, v[74:75] offset:3328
	ds_write_b64 v63, v[92:93] offset:3584
	ds_write_b64 v63, v[88:89] offset:3840
	ds_write_b64 v63, v[94:95] offset:4096
	ds_write_b64 v63, v[96:97] offset:4352
	v_mov_b32_e32 v72, v74
	v_mov_b32_e32 v73, v75
	v_lshlrev_b32_e32 v78, 16, v19
	v_and_b32_e32 v79, 0xffff0000, v19
	v_sub_f32_e32 v78, 1.0, v78
	v_sub_f32_e32 v79, 1.0, v79
	v_mul_f32_e32 v74, v72, v78
	v_mul_f32_e32 v75, v73, v79
	v_lshlrev_b32_e32 v88, 16, v21
	v_and_b32_e32 v89, 0xffff0000, v21
	v_rcp_f32_e32 v76, v74
	v_rcp_f32_e32 v77, v75
	v_mul_f32_e32 v88, v88, v72
	v_mul_f32_e32 v89, v89, v73
	v_lshlrev_b32_e32 v90, 16, v18
	v_and_b32_e32 v91, 0xffff0000, v18
	v_mul_f32_e32 v90, v90, v74
	v_mul_f32_e32 v91, v91, v75
	v_lshlrev_b32_e32 v92, 16, v20
	v_and_b32_e32 v93, 0xffff0000, v20
	v_mul_f32_e32 v92, v92, v76
	v_mul_f32_e32 v93, v93, v77
	v_lshlrev_b32_e32 v94, 16, v22
	v_and_b32_e32 v95, 0xffff0000, v22
	v_mul_f32_e32 v94, v94, v76
	v_mul_f32_e32 v95, v95, v77
	v_lshlrev_b32_e32 v96, 16, v23
	v_and_b32_e32 v97, 0xffff0000, v23
	ds_write_b64 v63, v[90:91] offset:4608
	ds_write_b64 v63, v[74:75] offset:4864
	ds_write_b64 v63, v[92:93] offset:5120
	ds_write_b64 v63, v[88:89] offset:5376
	ds_write_b64 v63, v[94:95] offset:5632
	ds_write_b64 v63, v[96:97] offset:5888
	v_mov_b32_e32 v72, v74
	v_mov_b32_e32 v73, v75

; __device__ __forceinline__ float allreduce16(float x) { x += dppf<0xB1>(x); x += dppf<0x4E>(x); x += dppf<0x141>(x); x += dppf<0x140>(x); return x; }
; template <int MODE>
; __device__ __forceinline__ void rwkv_scan_unit(int wid_s, const bf16* SIbh_, bf16* Yb_, int ystride, int quarter, float* ldsf) {
;     ...
;         if (wv < 4) {
;             if (ch < 128) {
;                 const float* B = ldsf + (ch & 3) * (16 * 384);
;                 float* PY = PYb + (ch & 1) * (16 * 260) + wv * 64 + lane;
;                 const float* q = B;
;                 f32x4 r4 = *(const f32x4*)(q + c4), om4 = *(const f32x4*)(q + 64 + c4), k4 = *(const f32x4*)(q + 128 + c4), kk4 = *(const f32x4*)(q + 192 + c4), ka4 = *(const f32x4*)(q + 256 + c4);
;                 float v = q[320 + rowl];
;                 __builtin_amdgcn_s_setprio(3);
; #pragma unroll
;                 for (int s = 0; s < 16; ++s) {
;                     const float* qn = B + ((MODE & 2) ? 0 : ((s + 1) & 15)) * 384;
;                     const f32x4 nr4 = *(const f32x4*)(qn + c4), nom4 = *(const f32x4*)(qn + 64 + c4), nk4 = *(const f32x4*)(qn + 128 + c4), nkk4 = *(const f32x4*)(qn + 192 + c4), nka4 = *(const f32x4*)(qn + 256 + c4);
;                     const float nv = qn[320 + rowl];
;                     const f32x2 pa = Sa * (f32x2){kk4.x, kk4.y} + Sb * (f32x2){kk4.z, kk4.w};
;                     const float sa = (MODE & 1) ? (pa.x + pa.y) : allreduce16(pa.x + pa.y);
;                     Sa = Sa - Sa * (f32x2){om4.x, om4.y} + (f32x2){k4.x, k4.y} * v; Sb = Sb - Sb * (f32x2){om4.z, om4.w} + (f32x2){k4.z, k4.w} * v;
;                     Sa = Sa - (f32x2){ka4.x, ka4.y} * sa; Sb = Sb - (f32x2){ka4.z, ka4.w} * sa;
;                     const f32x2 py = Sa * (f32x2){r4.x, r4.y} + Sb * (f32x2){r4.z, r4.w};
;                     PY[s * 260] = py.x + py.y;
;                     r4 = nr4; om4 = nom4; k4 = nk4; kk4 = nkk4; ka4 = nka4; v = nv;
;                 }
.LBB0_1412:
	s_andn2_saveexec_b64 s[8:9], s[8:9]
	s_cbranch_execz .LBB0_1401
	s_cmp_eq_u32 s6, 0x180000
	s_cbranch_scc1 .LBB0_1401
	s_and_b32 s10, s0, 3
	s_mulk_i32 s10, 0x6000
	v_lshl_add_u32 v105, v58, 2, s10
	v_lshl_add_u32 v107, v61, 2, s10
	s_add_i32 s11, s0, 1
	s_and_b32 s11, s11, 3
	s_mulk_i32 s11, 0x6000
	v_lshl_add_u32 v100, v58, 2, s11
	v_lshl_add_u32 v101, v61, 2, s11
	s_bitcmp1_b32 s0, 0
	s_cselect_b32 s10, 0x4100, 0
	v_add_u32_e32 v63, s10, v60
	s_setprio 3
	s_cmp_lg_u32 s0, 0
	s_cbranch_scc1 .Lmy_sc_main
	ds_read_b128 v[72:75], v105 offset:768
	ds_read_b128 v[68:71], v105 offset:512
	ds_read_b128 v[76:79], v105 offset:1024
	ds_read_b128 v[64:67], v105
	ds_read2st64_b32 v[32:33], v107 offset0:5 offset1:11
	ds_read_b128 v[92:95], v105 offset:2304
	ds_read_b128 v[88:91], v105 offset:2048
	ds_read_b128 v[96:99], v105 offset:2560
	ds_read_b128 v[84:87], v105 offset:1536
	s_waitcnt lgkmcnt(0)
	v_pk_mul_f32 v[28:29], v[54:55], v[72:73]
	v_pk_fma_f32 v[28:29], v[52:53], v[74:75], v[28:29]
	v_add_f32_e32 v28, v28, v29
	s_nop 1
.Lmy_sc_main:
	v_add_f32_dpp v28, v28, v28 quad_perm:[1,0,3,2] row_mask:0xf bank_mask:0xf bound_ctrl:1
	s_nop 1
	v_add_f32_dpp v28, v28, v28 quad_perm:[2,3,0,1] row_mask:0xf bank_mask:0xf bound_ctrl:1
	v_pk_fma_f32 v[24:25], v[68:69], v[32:33], v[54:55] op_sel_hi:[1,0,1]
	v_pk_fma_f32 v[26:27], v[70:71], v[32:33], v[52:53] op_sel_hi:[1,0,1]
	v_add_f32_dpp v28, v28, v28 row_half_mirror row_mask:0xf bank_mask:0xf bound_ctrl:1
	ds_read_b128 v[8:11], v105 offset:3840
	ds_read_b128 v[4:7], v105 offset:3584
	ds_read_b128 v[12:15], v105 offset:4096
	ds_read_b128 v[0:3], v105 offset:3072
	ds_read2st64_b32 v[34:35], v107 offset0:17 offset1:23
	s_waitcnt lgkmcnt(5)
	v_add_f32_dpp v28, v28, v28 row_mirror row_mask:0xf bank_mask:0xf bound_ctrl:1
	v_pk_fma_f32 v[24:25], v[76:77], v[28:29], v[24:25] op_sel_hi:[1,0,1] neg_lo:[1,0,0] neg_hi:[1,0,0]
	v_pk_fma_f32 v[26:27], v[78:79], v[28:29], v[26:27] op_sel_hi:[1,0,1] neg_lo:[1,0,0] neg_hi:[1,0,0]
	v_pk_mul_f32 v[28:29], v[24:25], v[92:93]
	v_pk_fma_f32 v[28:29], v[26:27], v[94:95], v[28:29]
	v_add_f32_e32 v28, v28, v29
	v_pk_mul_f32 v[30:31], v[66:67], v[26:27]
	v_pk_fma_f32 v[30:31], v[64:65], v[24:25], v[30:31]
	v_add_f32_dpp v28, v28, v28 quad_perm:[1,0,3,2] row_mask:0xf bank_mask:0xf bound_ctrl:1
	v_add_f32_e32 v30, v30, v31
	ds_write_b32 v63, v30
	v_add_f32_dpp v28, v28, v28 quad_perm:[2,3,0,1] row_mask:0xf bank_mask:0xf bound_ctrl:1
	v_pk_fma_f32 v[54:55], v[88:89], v[32:33], v[24:25] op_sel:[0,1,0] op_sel_hi:[1,1,1]
	v_pk_fma_f32 v[52:53], v[90:91], v[32:33], v[26:27] op_sel:[0,1,0] op_sel_hi:[1,1,1]
	v_add_f32_dpp v28, v28, v28 row_half_mirror row_mask:0xf bank_mask:0xf bound_ctrl:1
	ds_read_b128 v[40:43], v105 offset:5376
	ds_read_b128 v[20:23], v105 offset:5120
	ds_read_b128 v[44:47], v105 offset:5632
	ds_read_b128 v[16:19], v105 offset:4608
	s_waitcnt lgkmcnt(4)
	v_add_f32_dpp v28, v28, v28 row_mirror row_mask:0xf bank_mask:0xf bound_ctrl:1
	v_pk_fma_f32 v[54:55], v[96:97], v[28:29], v[54:55] op_sel_hi:[1,0,1] neg_lo:[1,0,0] neg_hi:[1,0,0]
	v_pk_fma_f32 v[52:53], v[98:99], v[28:29], v[52:53] op_sel_hi:[1,0,1] neg_lo:[1,0,0] neg_hi:[1,0,0]
	v_pk_mul_f32 v[28:29], v[54:55], v[8:9]
	v_pk_fma_f32 v[28:29], v[52:53], v[10:11], v[28:29]
	v_add_f32_e32 v28, v28, v29
	v_pk_mul_f32 v[30:31], v[86:87], v[52:53]
	v_pk_fma_f32 v[30:31], v[84:85], v[54:55], v[30:31]
	v_add_f32_dpp v28, v28, v28 quad_perm:[1,0,3,2] row_mask:0xf bank_mask:0xf bound_ctrl:1
	v_add_f32_e32 v30, v30, v31
	ds_write_b32 v63, v30 offset:1040
	v_add_f32_dpp v28, v28, v28 quad_perm:[2,3,0,1] row_mask:0xf bank_mask:0xf bound_ctrl:1
	v_pk_fma_f32 v[24:25], v[4:5], v[34:35], v[54:55] op_sel_hi:[1,0,1]
	v_pk_fma_f32 v[26:27], v[6:7], v[34:35], v[52:53] op_sel_hi:[1,0,1]
	v_add_f32_dpp v28, v28, v28 row_half_mirror row_mask:0xf bank_mask:0xf bound_ctrl:1
	ds_read_b128 v[72:75], v105 offset:6912
	ds_read_b128 v[68:71], v105 offset:6656
	ds_read_b128 v[76:79], v105 offset:7168
	ds_read_b128 v[64:67], v105 offset:6144
	ds_read2st64_b32 v[32:33], v107 offset0:29 offset1:35
	s_waitcnt lgkmcnt(5)
	v_add_f32_dpp v28, v28, v28 row_mirror row_mask:0xf bank_mask:0xf bound_ctrl:1
	v_pk_fma_f32 v[24:25], v[12:13], v[28:29], v[24:25] op_sel_hi:[1,0,1] neg_lo:[1,0,0] neg_hi:[1,0,0]
	v_pk_fma_f32 v[26:27], v[14:15], v[28:29], v[26:27] op_sel_hi:[1,0,1] neg_lo:[1,0,0] neg_hi:[1,0,0]
	v_pk_mul_f32 v[28:29], v[24:25], v[40:41]
	v_pk_fma_f32 v[28:29], v[26:27], v[42:43], v[28:29]
	v_add_f32_e32 v28, v28, v29
	v_pk_mul_f32 v[30:31], v[2:3], v[26:27]
	v_pk_fma_f32 v[30:31], v[0:1], v[24:25], v[30:31]
	v_add_f32_dpp v28, v28, v28 quad_perm:[1,0,3,2] row_mask:0xf bank_mask:0xf bound_ctrl:1
	v_add_f32_e32 v30, v30, v31
	ds_write_b32 v63, v30 offset:2080
	v_add_f32_dpp v28, v28, v28 quad_perm:[2,3,0,1] row_mask:0xf bank_mask:0xf bound_ctrl:1
	v_pk_fma_f32 v[54:55], v[20:21], v[34:35], v[24:25] op_sel:[0,1,0] op_sel_hi:[1,1,1]
	v_pk_fma_f32 v[52:53], v[22:23], v[34:35], v[26:27] op_sel:[0,1,0] op_sel_hi:[1,1,1]
	v_add_f32_dpp v28, v28, v28 row_half_mirror row_mask:0xf bank_mask:0xf bound_ctrl:1
	ds_read_b128 v[92:95], v105 offset:8448
	ds_read_b128 v[88:91], v105 offset:8192
	ds_read_b128 v[96:99], v105 offset:8704
	ds_read_b128 v[84:87], v105 offset:7680
	s_waitcnt lgkmcnt(4)
; __device__ __forceinline__ float allreduce16(float x) { x += dppf<0xB1>(x); x += dppf<0x4E>(x); x += dppf<0x141>(x); x += dppf<0x140>(x); return x; }
; template <int MODE>
; __device__ __forceinline__ void rwkv_scan_unit(int wid_s, const bf16* SIbh_, bf16* Yb_, int ystride, int quarter, float* ldsf) {
;     ...
;                 for (int s = 0; s < 16; ++s) {
;                     const float* qn = B + ((MODE & 2) ? 0 : ((s + 1) & 15)) * 384;
;                     const f32x4 nr4 = *(const f32x4*)(qn + c4), nom4 = *(const f32x4*)(qn + 64 + c4), nk4 = *(const f32x4*)(qn + 128 + c4), nkk4 = *(const f32x4*)(qn + 192 + c4), nka4 = *(const f32x4*)(qn + 256 + c4);
;                     const float nv = qn[320 + rowl];
;                     const f32x2 pa = Sa * (f32x2){kk4.x, kk4.y} + Sb * (f32x2){kk4.z, kk4.w};
;                     const float sa = (MODE & 1) ? (pa.x + pa.y) : allreduce16(pa.x + pa.y);
;                     Sa = Sa - Sa * (f32x2){om4.x, om4.y} + (f32x2){k4.x, k4.y} * v; Sb = Sb - Sb * (f32x2){om4.z, om4.w} + (f32x2){k4.z, k4.w} * v;
;                     Sa = Sa - (f32x2){ka4.x, ka4.y} * sa; Sb = Sb - (f32x2){ka4.z, ka4.w} * sa;
;                     const f32x2 py = Sa * (f32x2){r4.x, r4.y} + Sb * (f32x2){r4.z, r4.w};
;                     PY[s * 260] = py.x + py.y;
;                     r4 = nr4; om4 = nom4; k4 = nk4; kk4 = nkk4; ka4 = nka4; v = nv;
;                 }
	v_add_f32_dpp v28, v28, v28 row_mirror row_mask:0xf bank_mask:0xf bound_ctrl:1
	v_pk_fma_f32 v[54:55], v[44:45], v[28:29], v[54:55] op_sel_hi:[1,0,1] neg_lo:[1,0,0] neg_hi:[1,0,0]
	v_pk_fma_f32 v[52:53], v[46:47], v[28:29], v[52:53] op_sel_hi:[1,0,1] neg_lo:[1,0,0] neg_hi:[1,0,0]
	v_pk_mul_f32 v[28:29], v[54:55], v[72:73]
	v_pk_fma_f32 v[28:29], v[52:53], v[74:75], v[28:29]
	v_add_f32_e32 v28, v28, v29
	v_pk_mul_f32 v[30:31], v[18:19], v[52:53]
	v_pk_fma_f32 v[30:31], v[16:17], v[54:55], v[30:31]
	v_add_f32_dpp v28, v28, v28 quad_perm:[1,0,3,2] row_mask:0xf bank_mask:0xf bound_ctrl:1
	v_add_f32_e32 v30, v30, v31
	ds_write_b32 v63, v30 offset:3120
	v_add_f32_dpp v28, v28, v28 quad_perm:[2,3,0,1] row_mask:0xf bank_mask:0xf bound_ctrl:1
	v_pk_fma_f32 v[24:25], v[68:69], v[32:33], v[54:55] op_sel_hi:[1,0,1]
	v_pk_fma_f32 v[26:27], v[70:71], v[32:33], v[52:53] op_sel_hi:[1,0,1]
	v_add_f32_dpp v28, v28, v28 row_half_mirror row_mask:0xf bank_mask:0xf bound_ctrl:1
	ds_read_b128 v[8:11], v105 offset:9984
	ds_read_b128 v[4:7], v105 offset:9728
	ds_read_b128 v[12:15], v105 offset:10240
	ds_read_b128 v[0:3], v105 offset:9216
	ds_read2st64_b32 v[34:35], v107 offset0:41 offset1:47
	s_waitcnt lgkmcnt(5)
	v_add_f32_dpp v28, v28, v28 row_mirror row_mask:0xf bank_mask:0xf bound_ctrl:1
	v_pk_fma_f32 v[24:25], v[76:77], v[28:29], v[24:25] op_sel_hi:[1,0,1] neg_lo:[1,0,0] neg_hi:[1,0,0]
	v_pk_fma_f32 v[26:27], v[78:79], v[28:29], v[26:27] op_sel_hi:[1,0,1] neg_lo:[1,0,0] neg_hi:[1,0,0]
	v_pk_mul_f32 v[28:29], v[24:25], v[92:93]
	v_pk_fma_f32 v[28:29], v[26:27], v[94:95], v[28:29]
	v_add_f32_e32 v28, v28, v29
	v_pk_mul_f32 v[30:31], v[66:67], v[26:27]
	v_pk_fma_f32 v[30:31], v[64:65], v[24:25], v[30:31]
	v_add_f32_dpp v28, v28, v28 quad_perm:[1,0,3,2] row_mask:0xf bank_mask:0xf bound_ctrl:1
	v_add_f32_e32 v30, v30, v31
	ds_write_b32 v63, v30 offset:4160
	v_add_f32_dpp v28, v28, v28 quad_perm:[2,3,0,1] row_mask:0xf bank_mask:0xf bound_ctrl:1
	v_pk_fma_f32 v[54:55], v[88:89], v[32:33], v[24:25] op_sel:[0,1,0] op_sel_hi:[1,1,1]
	v_pk_fma_f32 v[52:53], v[90:91], v[32:33], v[26:27] op_sel:[0,1,0] op_sel_hi:[1,1,1]
	v_add_f32_dpp v28, v28, v28 row_half_mirror row_mask:0xf bank_mask:0xf bound_ctrl:1
	ds_read_b128 v[40:43], v105 offset:11520
	ds_read_b128 v[20:23], v105 offset:11264
	ds_read_b128 v[44:47], v105 offset:11776
	ds_read_b128 v[16:19], v105 offset:10752
	s_waitcnt lgkmcnt(4)
	v_add_f32_dpp v28, v28, v28 row_mirror row_mask:0xf bank_mask:0xf bound_ctrl:1
	v_pk_fma_f32 v[54:55], v[96:97], v[28:29], v[54:55] op_sel_hi:[1,0,1] neg_lo:[1,0,0] neg_hi:[1,0,0]
	v_pk_fma_f32 v[52:53], v[98:99], v[28:29], v[52:53] op_sel_hi:[1,0,1] neg_lo:[1,0,0] neg_hi:[1,0,0]
	v_pk_mul_f32 v[28:29], v[54:55], v[8:9]
	v_pk_fma_f32 v[28:29], v[52:53], v[10:11], v[28:29]
	v_add_f32_e32 v28, v28, v29
	v_pk_mul_f32 v[30:31], v[86:87], v[52:53]
	v_pk_fma_f32 v[30:31], v[84:85], v[54:55], v[30:31]
	v_add_f32_dpp v28, v28, v28 quad_perm:[1,0,3,2] row_mask:0xf bank_mask:0xf bound_ctrl:1
	v_add_f32_e32 v30, v30, v31
	ds_write_b32 v63, v30 offset:5200
	v_add_f32_dpp v28, v28, v28 quad_perm:[2,3,0,1] row_mask:0xf bank_mask:0xf bound_ctrl:1
	v_pk_fma_f32 v[24:25], v[4:5], v[34:35], v[54:55] op_sel_hi:[1,0,1]
	v_pk_fma_f32 v[26:27], v[6:7], v[34:35], v[52:53] op_sel_hi:[1,0,1]
	v_add_f32_dpp v28, v28, v28 row_half_mirror row_mask:0xf bank_mask:0xf bound_ctrl:1
	ds_read_b128 v[72:75], v105 offset:13056
	ds_read_b128 v[68:71], v105 offset:12800
	ds_read_b128 v[76:79], v105 offset:13312
	ds_read_b128 v[64:67], v105 offset:12288
	ds_read2st64_b32 v[32:33], v107 offset0:53 offset1:59
	s_waitcnt lgkmcnt(5)
	v_add_f32_dpp v28, v28, v28 row_mirror row_mask:0xf bank_mask:0xf bound_ctrl:1
	v_pk_fma_f32 v[24:25], v[12:13], v[28:29], v[24:25] op_sel_hi:[1,0,1] neg_lo:[1,0,0] neg_hi:[1,0,0]
	v_pk_fma_f32 v[26:27], v[14:15], v[28:29], v[26:27] op_sel_hi:[1,0,1] neg_lo:[1,0,0] neg_hi:[1,0,0]
	v_pk_mul_f32 v[28:29], v[24:25], v[40:41]
	v_pk_fma_f32 v[28:29], v[26:27], v[42:43], v[28:29]
	v_add_f32_e32 v28, v28, v29
	v_pk_mul_f32 v[30:31], v[2:3], v[26:27]
	v_pk_fma_f32 v[30:31], v[0:1], v[24:25], v[30:31]
	v_add_f32_dpp v28, v28, v28 quad_perm:[1,0,3,2] row_mask:0xf bank_mask:0xf bound_ctrl:1
	v_add_f32_e32 v30, v30, v31
	ds_write_b32 v63, v30 offset:6240
	v_add_f32_dpp v28, v28, v28 quad_perm:[2,3,0,1] row_mask:0xf bank_mask:0xf bound_ctrl:1
	v_pk_fma_f32 v[54:55], v[20:21], v[34:35], v[24:25] op_sel:[0,1,0] op_sel_hi:[1,1,1]
	v_pk_fma_f32 v[52:53], v[22:23], v[34:35], v[26:27] op_sel:[0,1,0] op_sel_hi:[1,1,1]
	v_add_f32_dpp v28, v28, v28 row_half_mirror row_mask:0xf bank_mask:0xf bound_ctrl:1
	ds_read_b128 v[92:95], v105 offset:14592
	ds_read_b128 v[88:91], v105 offset:14336
	ds_read_b128 v[96:99], v105 offset:14848
	ds_read_b128 v[84:87], v105 offset:13824
	s_waitcnt lgkmcnt(4)
	v_add_f32_dpp v28, v28, v28 row_mirror row_mask:0xf bank_mask:0xf bound_ctrl:1
	v_pk_fma_f32 v[54:55], v[44:45], v[28:29], v[54:55] op_sel_hi:[1,0,1] neg_lo:[1,0,0] neg_hi:[1,0,0]
	v_pk_fma_f32 v[52:53], v[46:47], v[28:29], v[52:53] op_sel_hi:[1,0,1] neg_lo:[1,0,0] neg_hi:[1,0,0]
	v_pk_mul_f32 v[28:29], v[54:55], v[72:73]
	v_pk_fma_f32 v[28:29], v[52:53], v[74:75], v[28:29]
	v_add_f32_e32 v28, v28, v29
	v_pk_mul_f32 v[30:31], v[18:19], v[52:53]
	v_pk_fma_f32 v[30:31], v[16:17], v[54:55], v[30:31]
	v_add_f32_dpp v28, v28, v28 quad_perm:[1,0,3,2] row_mask:0xf bank_mask:0xf bound_ctrl:1
	v_add_f32_e32 v30, v30, v31
	ds_write_b32 v63, v30 offset:7280
	v_add_f32_dpp v28, v28, v28 quad_perm:[2,3,0,1] row_mask:0xf bank_mask:0xf bound_ctrl:1
	v_pk_fma_f32 v[24:25], v[68:69], v[32:33], v[54:55] op_sel_hi:[1,0,1]
	v_pk_fma_f32 v[26:27], v[70:71], v[32:33], v[52:53] op_sel_hi:[1,0,1]
	v_add_f32_dpp v28, v28, v28 row_half_mirror row_mask:0xf bank_mask:0xf bound_ctrl:1
	ds_read_b128 v[8:11], v105 offset:16128
	ds_read_b128 v[4:7], v105 offset:15872
	ds_read_b128 v[12:15], v105 offset:16384
	ds_read_b128 v[0:3], v105 offset:15360
	ds_read2st64_b32 v[34:35], v107 offset0:65 offset1:71
	s_waitcnt lgkmcnt(5)
; __device__ __forceinline__ float allreduce16(float x) { x += dppf<0xB1>(x); x += dppf<0x4E>(x); x += dppf<0x141>(x); x += dppf<0x140>(x); return x; }
; template <int MODE>
; __device__ __forceinline__ void rwkv_scan_unit(int wid_s, const bf16* SIbh_, bf16* Yb_, int ystride, int quarter, float* ldsf) {
;     ...
;                 for (int s = 0; s < 16; ++s) {
;                     const float* qn = B + ((MODE & 2) ? 0 : ((s + 1) & 15)) * 384;
;                     const f32x4 nr4 = *(const f32x4*)(qn + c4), nom4 = *(const f32x4*)(qn + 64 + c4), nk4 = *(const f32x4*)(qn + 128 + c4), nkk4 = *(const f32x4*)(qn + 192 + c4), nka4 = *(const f32x4*)(qn + 256 + c4);
;                     const float nv = qn[320 + rowl];
;                     const f32x2 pa = Sa * (f32x2){kk4.x, kk4.y} + Sb * (f32x2){kk4.z, kk4.w};
;                     const float sa = (MODE & 1) ? (pa.x + pa.y) : allreduce16(pa.x + pa.y);
;                     Sa = Sa - Sa * (f32x2){om4.x, om4.y} + (f32x2){k4.x, k4.y} * v; Sb = Sb - Sb * (f32x2){om4.z, om4.w} + (f32x2){k4.z, k4.w} * v;
;                     Sa = Sa - (f32x2){ka4.x, ka4.y} * sa; Sb = Sb - (f32x2){ka4.z, ka4.w} * sa;
;                     const f32x2 py = Sa * (f32x2){r4.x, r4.y} + Sb * (f32x2){r4.z, r4.w};
;                     PY[s * 260] = py.x + py.y;
;                     r4 = nr4; om4 = nom4; k4 = nk4; kk4 = nkk4; ka4 = nka4; v = nv;
;                 }
	v_add_f32_dpp v28, v28, v28 row_mirror row_mask:0xf bank_mask:0xf bound_ctrl:1
	v_pk_fma_f32 v[24:25], v[76:77], v[28:29], v[24:25] op_sel_hi:[1,0,1] neg_lo:[1,0,0] neg_hi:[1,0,0]
	v_pk_fma_f32 v[26:27], v[78:79], v[28:29], v[26:27] op_sel_hi:[1,0,1] neg_lo:[1,0,0] neg_hi:[1,0,0]
	v_pk_mul_f32 v[28:29], v[24:25], v[92:93]
	v_pk_fma_f32 v[28:29], v[26:27], v[94:95], v[28:29]
	v_add_f32_e32 v28, v28, v29
	v_pk_mul_f32 v[30:31], v[66:67], v[26:27]
	v_pk_fma_f32 v[30:31], v[64:65], v[24:25], v[30:31]
	v_add_f32_dpp v28, v28, v28 quad_perm:[1,0,3,2] row_mask:0xf bank_mask:0xf bound_ctrl:1
	v_add_f32_e32 v30, v30, v31
	ds_write_b32 v63, v30 offset:8320
	v_add_f32_dpp v28, v28, v28 quad_perm:[2,3,0,1] row_mask:0xf bank_mask:0xf bound_ctrl:1
	v_pk_fma_f32 v[54:55], v[88:89], v[32:33], v[24:25] op_sel:[0,1,0] op_sel_hi:[1,1,1]
	v_pk_fma_f32 v[52:53], v[90:91], v[32:33], v[26:27] op_sel:[0,1,0] op_sel_hi:[1,1,1]
	v_add_f32_dpp v28, v28, v28 row_half_mirror row_mask:0xf bank_mask:0xf bound_ctrl:1
	ds_read_b128 v[40:43], v105 offset:17664
	ds_read_b128 v[20:23], v105 offset:17408
	ds_read_b128 v[44:47], v105 offset:17920
	ds_read_b128 v[16:19], v105 offset:16896
	s_waitcnt lgkmcnt(4)
	v_add_f32_dpp v28, v28, v28 row_mirror row_mask:0xf bank_mask:0xf bound_ctrl:1
	v_pk_fma_f32 v[54:55], v[96:97], v[28:29], v[54:55] op_sel_hi:[1,0,1] neg_lo:[1,0,0] neg_hi:[1,0,0]
	v_pk_fma_f32 v[52:53], v[98:99], v[28:29], v[52:53] op_sel_hi:[1,0,1] neg_lo:[1,0,0] neg_hi:[1,0,0]
	v_pk_mul_f32 v[28:29], v[54:55], v[8:9]
	v_pk_fma_f32 v[28:29], v[52:53], v[10:11], v[28:29]
	v_add_f32_e32 v28, v28, v29
	v_pk_mul_f32 v[30:31], v[86:87], v[52:53]
	v_pk_fma_f32 v[30:31], v[84:85], v[54:55], v[30:31]
	v_add_f32_dpp v28, v28, v28 quad_perm:[1,0,3,2] row_mask:0xf bank_mask:0xf bound_ctrl:1
	v_add_f32_e32 v30, v30, v31
	ds_write_b32 v63, v30 offset:9360
	v_add_f32_dpp v28, v28, v28 quad_perm:[2,3,0,1] row_mask:0xf bank_mask:0xf bound_ctrl:1
	v_pk_fma_f32 v[24:25], v[4:5], v[34:35], v[54:55] op_sel_hi:[1,0,1]
	v_pk_fma_f32 v[26:27], v[6:7], v[34:35], v[52:53] op_sel_hi:[1,0,1]
	v_add_f32_dpp v28, v28, v28 row_half_mirror row_mask:0xf bank_mask:0xf bound_ctrl:1
	ds_read_b128 v[72:75], v105 offset:19200
	ds_read_b128 v[68:71], v105 offset:18944
	ds_read_b128 v[76:79], v105 offset:19456
	ds_read_b128 v[64:67], v105 offset:18432
	ds_read2st64_b32 v[32:33], v107 offset0:77 offset1:83
	s_waitcnt lgkmcnt(5)
	v_add_f32_dpp v28, v28, v28 row_mirror row_mask:0xf bank_mask:0xf bound_ctrl:1
	v_pk_fma_f32 v[24:25], v[12:13], v[28:29], v[24:25] op_sel_hi:[1,0,1] neg_lo:[1,0,0] neg_hi:[1,0,0]
	v_pk_fma_f32 v[26:27], v[14:15], v[28:29], v[26:27] op_sel_hi:[1,0,1] neg_lo:[1,0,0] neg_hi:[1,0,0]
	v_pk_mul_f32 v[28:29], v[24:25], v[40:41]
	v_pk_fma_f32 v[28:29], v[26:27], v[42:43], v[28:29]
	v_add_f32_e32 v28, v28, v29
	v_pk_mul_f32 v[30:31], v[2:3], v[26:27]
	v_pk_fma_f32 v[30:31], v[0:1], v[24:25], v[30:31]
	v_add_f32_dpp v28, v28, v28 quad_perm:[1,0,3,2] row_mask:0xf bank_mask:0xf bound_ctrl:1
	v_add_f32_e32 v30, v30, v31
	ds_write_b32 v63, v30 offset:10400
	v_add_f32_dpp v28, v28, v28 quad_perm:[2,3,0,1] row_mask:0xf bank_mask:0xf bound_ctrl:1
	v_pk_fma_f32 v[54:55], v[20:21], v[34:35], v[24:25] op_sel:[0,1,0] op_sel_hi:[1,1,1]
	v_pk_fma_f32 v[52:53], v[22:23], v[34:35], v[26:27] op_sel:[0,1,0] op_sel_hi:[1,1,1]
	v_add_f32_dpp v28, v28, v28 row_half_mirror row_mask:0xf bank_mask:0xf bound_ctrl:1
	ds_read_b128 v[92:95], v105 offset:20736
	ds_read_b128 v[88:91], v105 offset:20480
	ds_read_b128 v[96:99], v105 offset:20992
	ds_read_b128 v[84:87], v105 offset:19968
	s_waitcnt lgkmcnt(4)
	v_add_f32_dpp v28, v28, v28 row_mirror row_mask:0xf bank_mask:0xf bound_ctrl:1
	v_pk_fma_f32 v[54:55], v[44:45], v[28:29], v[54:55] op_sel_hi:[1,0,1] neg_lo:[1,0,0] neg_hi:[1,0,0]
	v_pk_fma_f32 v[52:53], v[46:47], v[28:29], v[52:53] op_sel_hi:[1,0,1] neg_lo:[1,0,0] neg_hi:[1,0,0]
	v_pk_mul_f32 v[28:29], v[54:55], v[72:73]
	v_pk_fma_f32 v[28:29], v[52:53], v[74:75], v[28:29]
	v_add_f32_e32 v28, v28, v29
	v_pk_mul_f32 v[30:31], v[18:19], v[52:53]
	v_pk_fma_f32 v[30:31], v[16:17], v[54:55], v[30:31]
	v_add_f32_dpp v28, v28, v28 quad_perm:[1,0,3,2] row_mask:0xf bank_mask:0xf bound_ctrl:1
	v_add_f32_e32 v30, v30, v31
	ds_write_b32 v63, v30 offset:11440
	v_add_f32_dpp v28, v28, v28 quad_perm:[2,3,0,1] row_mask:0xf bank_mask:0xf bound_ctrl:1
	v_pk_fma_f32 v[24:25], v[68:69], v[32:33], v[54:55] op_sel_hi:[1,0,1]
	v_pk_fma_f32 v[26:27], v[70:71], v[32:33], v[52:53] op_sel_hi:[1,0,1]
	v_add_f32_dpp v28, v28, v28 row_half_mirror row_mask:0xf bank_mask:0xf bound_ctrl:1
	ds_read_b128 v[8:11], v105 offset:22272
	ds_read_b128 v[4:7], v105 offset:22016
	ds_read_b128 v[12:15], v105 offset:22528
	ds_read_b128 v[0:3], v105 offset:21504
	ds_read2st64_b32 v[34:35], v107 offset0:89 offset1:95
	s_waitcnt lgkmcnt(5)
; __device__ __forceinline__ float allreduce16(float x) { x += dppf<0xB1>(x); x += dppf<0x4E>(x); x += dppf<0x141>(x); x += dppf<0x140>(x); return x; }
; template <int MODE>
; __device__ __forceinline__ void rwkv_scan_unit(int wid_s, const bf16* SIbh_, bf16* Yb_, int ystride, int quarter, float* ldsf) {
;     ...
;                 f32x4 r4 = *(const f32x4*)(q + c4), om4 = *(const f32x4*)(q + 64 + c4), k4 = *(const f32x4*)(q + 128 + c4), kk4 = *(const f32x4*)(q + 192 + c4), ka4 = *(const f32x4*)(q + 256 + c4);
;                 float v = q[320 + rowl];
;                 __builtin_amdgcn_s_setprio(3);
; #pragma unroll
;                 for (int s = 0; s < 16; ++s) {
;                     const float* qn = B + ((MODE & 2) ? 0 : ((s + 1) & 15)) * 384;
;                     const f32x4 nr4 = *(const f32x4*)(qn + c4), nom4 = *(const f32x4*)(qn + 64 + c4), nk4 = *(const f32x4*)(qn + 128 + c4), nkk4 = *(const f32x4*)(qn + 192 + c4), nka4 = *(const f32x4*)(qn + 256 + c4);
;                     const float nv = qn[320 + rowl];
;                     const f32x2 pa = Sa * (f32x2){kk4.x, kk4.y} + Sb * (f32x2){kk4.z, kk4.w};
;                     const float sa = (MODE & 1) ? (pa.x + pa.y) : allreduce16(pa.x + pa.y);
;                     Sa = Sa - Sa * (f32x2){om4.x, om4.y} + (f32x2){k4.x, k4.y} * v; Sb = Sb - Sb * (f32x2){om4.z, om4.w} + (f32x2){k4.z, k4.w} * v;
;                     Sa = Sa - (f32x2){ka4.x, ka4.y} * sa; Sb = Sb - (f32x2){ka4.z, ka4.w} * sa;
;                     const f32x2 py = Sa * (f32x2){r4.x, r4.y} + Sb * (f32x2){r4.z, r4.w};
;                     PY[s * 260] = py.x + py.y;
;                     r4 = nr4; om4 = nom4; k4 = nk4; kk4 = nkk4; ka4 = nka4; v = nv;
;                 }
;                 __builtin_amdgcn_s_setprio(0);
	v_add_f32_dpp v28, v28, v28 row_mirror row_mask:0xf bank_mask:0xf bound_ctrl:1
	v_pk_fma_f32 v[24:25], v[76:77], v[28:29], v[24:25] op_sel_hi:[1,0,1] neg_lo:[1,0,0] neg_hi:[1,0,0]
	v_pk_fma_f32 v[26:27], v[78:79], v[28:29], v[26:27] op_sel_hi:[1,0,1] neg_lo:[1,0,0] neg_hi:[1,0,0]
	v_pk_mul_f32 v[28:29], v[24:25], v[92:93]
	v_pk_fma_f32 v[28:29], v[26:27], v[94:95], v[28:29]
	v_add_f32_e32 v28, v28, v29
	v_pk_mul_f32 v[30:31], v[66:67], v[26:27]
	v_pk_fma_f32 v[30:31], v[64:65], v[24:25], v[30:31]
	v_add_f32_dpp v28, v28, v28 quad_perm:[1,0,3,2] row_mask:0xf bank_mask:0xf bound_ctrl:1
	v_add_f32_e32 v30, v30, v31
	ds_write_b32 v63, v30 offset:12480
	v_add_f32_dpp v28, v28, v28 quad_perm:[2,3,0,1] row_mask:0xf bank_mask:0xf bound_ctrl:1
	v_pk_fma_f32 v[54:55], v[88:89], v[32:33], v[24:25] op_sel:[0,1,0] op_sel_hi:[1,1,1]
	v_pk_fma_f32 v[52:53], v[90:91], v[32:33], v[26:27] op_sel:[0,1,0] op_sel_hi:[1,1,1]
	v_add_f32_dpp v28, v28, v28 row_half_mirror row_mask:0xf bank_mask:0xf bound_ctrl:1
	ds_read_b128 v[40:43], v105 offset:23808
	ds_read_b128 v[20:23], v105 offset:23552
	ds_read_b128 v[44:47], v105 offset:24064
	ds_read_b128 v[16:19], v105 offset:23040
	ds_read_b128 v[36:39], v105 offset:23296
	s_waitcnt lgkmcnt(5)
	v_add_f32_dpp v28, v28, v28 row_mirror row_mask:0xf bank_mask:0xf bound_ctrl:1
	v_pk_fma_f32 v[54:55], v[96:97], v[28:29], v[54:55] op_sel_hi:[1,0,1] neg_lo:[1,0,0] neg_hi:[1,0,0]
	v_pk_fma_f32 v[52:53], v[98:99], v[28:29], v[52:53] op_sel_hi:[1,0,1] neg_lo:[1,0,0] neg_hi:[1,0,0]
	v_pk_mul_f32 v[28:29], v[54:55], v[8:9]
	v_pk_fma_f32 v[28:29], v[52:53], v[10:11], v[28:29]
	v_add_f32_e32 v28, v28, v29
	v_pk_mul_f32 v[30:31], v[86:87], v[52:53]
	v_pk_fma_f32 v[30:31], v[84:85], v[54:55], v[30:31]
	v_add_f32_dpp v28, v28, v28 quad_perm:[1,0,3,2] row_mask:0xf bank_mask:0xf bound_ctrl:1
	v_add_f32_e32 v30, v30, v31
	ds_write_b32 v63, v30 offset:13520
	v_add_f32_dpp v28, v28, v28 quad_perm:[2,3,0,1] row_mask:0xf bank_mask:0xf bound_ctrl:1
	v_pk_fma_f32 v[24:25], v[4:5], v[34:35], v[54:55] op_sel_hi:[1,0,1]
	v_pk_fma_f32 v[26:27], v[6:7], v[34:35], v[52:53] op_sel_hi:[1,0,1]
	v_add_f32_dpp v28, v28, v28 row_half_mirror row_mask:0xf bank_mask:0xf bound_ctrl:1
	ds_read_b128 v[72:75], v100 offset:768
	ds_read_b128 v[68:71], v100 offset:512
	ds_read_b128 v[76:79], v100 offset:1024
	ds_read_b128 v[64:67], v100
	ds_read2st64_b32 v[32:33], v101 offset0:5 offset1:11
	s_waitcnt lgkmcnt(5)
	v_add_f32_dpp v28, v28, v28 row_mirror row_mask:0xf bank_mask:0xf bound_ctrl:1
	v_pk_fma_f32 v[24:25], v[12:13], v[28:29], v[24:25] op_sel_hi:[1,0,1] neg_lo:[1,0,0] neg_hi:[1,0,0]
	v_pk_fma_f32 v[26:27], v[14:15], v[28:29], v[26:27] op_sel_hi:[1,0,1] neg_lo:[1,0,0] neg_hi:[1,0,0]
	v_pk_mul_f32 v[28:29], v[24:25], v[40:41]
	v_pk_fma_f32 v[28:29], v[26:27], v[42:43], v[28:29]
	v_add_f32_e32 v28, v28, v29
	v_pk_mul_f32 v[30:31], v[2:3], v[26:27]
	v_pk_fma_f32 v[30:31], v[0:1], v[24:25], v[30:31]
	v_add_f32_dpp v28, v28, v28 quad_perm:[1,0,3,2] row_mask:0xf bank_mask:0xf bound_ctrl:1
	v_add_f32_e32 v30, v30, v31
	ds_write_b32 v63, v30 offset:14560
	v_add_f32_dpp v28, v28, v28 quad_perm:[2,3,0,1] row_mask:0xf bank_mask:0xf bound_ctrl:1
	v_pk_fma_f32 v[54:55], v[20:21], v[34:35], v[24:25] op_sel:[0,1,0] op_sel_hi:[1,1,1]
	v_pk_fma_f32 v[52:53], v[22:23], v[34:35], v[26:27] op_sel:[0,1,0] op_sel_hi:[1,1,1]
	v_add_f32_dpp v28, v28, v28 row_half_mirror row_mask:0xf bank_mask:0xf bound_ctrl:1
	ds_read_b128 v[92:95], v100 offset:2304
	ds_read_b128 v[88:91], v100 offset:2048
	ds_read_b128 v[96:99], v100 offset:2560
	ds_read_b128 v[84:87], v100 offset:1536
	s_waitcnt lgkmcnt(4)
	v_add_f32_dpp v28, v28, v28 row_mirror row_mask:0xf bank_mask:0xf bound_ctrl:1
	v_pk_fma_f32 v[54:55], v[44:45], v[28:29], v[54:55] op_sel_hi:[1,0,1] neg_lo:[1,0,0] neg_hi:[1,0,0]
	v_pk_fma_f32 v[52:53], v[46:47], v[28:29], v[52:53] op_sel_hi:[1,0,1] neg_lo:[1,0,0] neg_hi:[1,0,0]
	v_pk_mul_f32 v[30:31], v[18:19], v[52:53]
	v_pk_fma_f32 v[30:31], v[16:17], v[54:55], v[30:31]
	v_pk_mul_f32 v[54:55], v[54:55], v[36:37]
	v_pk_mul_f32 v[52:53], v[52:53], v[38:39]
	v_add_f32_e32 v30, v30, v31
	ds_write_b32 v63, v30 offset:15600
	v_pk_mul_f32 v[28:29], v[54:55], v[72:73]
	v_pk_fma_f32 v[28:29], v[52:53], v[74:75], v[28:29]
	v_add_f32_e32 v28, v28, v29
	s_setprio 0
	s_branch .LBB0_1401
